# RmsStats panel-counter poll interval s_sleep 2 -> 8 (fewer loads of a word under atomic adds); otherwise v132
# baseline (speedup 1.0000x reference)
;     __device__ __forceinline__ bool run(const f32x4 (&v)[2][2][4][2], const Unit& u, int wr, int wc, int fr, int fq, PG8_LAS unsigned char* lds, int wid, int lane) const {
;     ...
;             bool dead = false; const unsigned long long t0 = __builtin_amdgcn_s_memrealtime(); const unsigned want = 32u;
;             for (;;) {
;                 if ((unsigned)__builtin_amdgcn_readfirstlane(__hip_atomic_load(cnt + 64 * u.pm, __ATOMIC_RELAXED, __HIP_MEMORY_SCOPE_AGENT)) >= want) break;
;                 if (__builtin_amdgcn_s_memrealtime() - t0 > 2000000ull) { if (lane == 0) __hip_atomic_store(tmo, 1u, __ATOMIC_RELAXED, __HIP_MEMORY_SCOPE_AGENT); dead = true; break; }
;                 __builtin_amdgcn_s_sleep(2);
;             }
.LBB0_831:
	global_load_dword v132, v149, s[16:17] sc1
	s_mov_b64 s[20:21], -1
	s_waitcnt vmcnt(0)
	v_readfirstlane_b32 s22, v132
	s_cmp_gt_u32 s22, 31
	s_mov_b64 s[22:23], -1
	s_cbranch_scc1 .LBB0_830
	s_memrealtime s[20:21]
	s_waitcnt lgkmcnt(0)
	s_sub_u32 s20, s20, s18
	s_subb_u32 s21, s21, s19
	v_cmp_lt_u64_e32 vcc, s[20:21], v[150:151]
	s_cbranch_vccz .LBB0_829
	s_mov_b64 s[22:23], 0
	s_sleep 8
	s_branch .LBB0_829
